# stack: norm1 modulation-vector wait sunk to first use (guarded), grid-barrier ops as global_, O_PMIX gain-vector reloads hoisted
# baseline (speedup 1.0000x reference)
.LBB0_148:
	s_waitcnt vmcnt(24)
	v_pk_mul_f32 v[148:149], v[30:31], v[30:31]
	v_pk_mul_f32 v[150:151], v[32:33], v[32:33]
	v_add_f32_e32 v147, v148, v149
	v_add_f32_e32 v147, v147, v150
	v_pk_mul_f32 v[152:153], v[26:27], v[26:27]
	v_add_f32_e32 v147, v151, v147
	v_add_f32_e32 v147, v152, v147
	v_pk_mul_f32 v[154:155], v[28:29], v[28:29]
	v_add_f32_e32 v147, v153, v147
	v_add_f32_e32 v147, v154, v147
	v_pk_mul_f32 v[156:157], v[22:23], v[22:23]
	v_add_f32_e32 v147, v155, v147
	v_add_f32_e32 v147, v156, v147
	v_pk_mul_f32 v[158:159], v[24:25], v[24:25]
	v_add_f32_e32 v147, v157, v147
	v_add_f32_e32 v147, v158, v147
	v_pk_mul_f32 v[160:161], v[18:19], v[18:19]
	v_add_f32_e32 v147, v159, v147
	v_add_f32_e32 v147, v160, v147
	v_pk_mul_f32 v[162:163], v[20:21], v[20:21]
	v_add_f32_e32 v147, v161, v147
	v_add_f32_e32 v147, v162, v147
	v_pk_mul_f32 v[164:165], v[14:15], v[14:15]
	v_add_f32_e32 v147, v163, v147
	v_add_f32_e32 v147, v164, v147
	v_pk_mul_f32 v[166:167], v[16:17], v[16:17]
	v_add_f32_e32 v147, v165, v147
	v_add_f32_e32 v147, v166, v147
	v_pk_mul_f32 v[168:169], v[10:11], v[10:11]
	v_add_f32_e32 v147, v167, v147
	v_add_f32_e32 v147, v168, v147
	v_pk_mul_f32 v[170:171], v[12:13], v[12:13]
	v_add_f32_e32 v147, v169, v147
	v_add_f32_e32 v147, v170, v147
	v_pk_mul_f32 v[172:173], v[6:7], v[6:7]
	v_add_f32_e32 v147, v171, v147
	v_add_f32_e32 v147, v172, v147
	v_pk_mul_f32 v[174:175], v[8:9], v[8:9]
	v_add_f32_e32 v147, v173, v147
	v_add_f32_e32 v147, v174, v147
	v_pk_mul_f32 v[176:177], v[2:3], v[2:3]
	v_add_f32_e32 v147, v175, v147
	v_add_f32_e32 v147, v176, v147
	v_pk_mul_f32 v[178:179], v[4:5], v[4:5]
	v_add_f32_e32 v147, v177, v147
	v_add_f32_e32 v147, v178, v147
	v_add_f32_e32 v147, v179, v147
	s_add_i32 s6, s6, s82
	s_cmpk_lt_i32 s6, 0x2800
	v_add_f32_dpp v147, v147, v147 quad_perm:[1,0,3,2] row_mask:0xf bank_mask:0xf bound_ctrl:1
	s_nop 1
	v_add_f32_dpp v147, v147, v147 quad_perm:[2,3,0,1] row_mask:0xf bank_mask:0xf bound_ctrl:1
	s_nop 1
	v_add_f32_dpp v147, v147, v147 row_half_mirror row_mask:0xf bank_mask:0xf bound_ctrl:1
	s_nop 1
	v_add_f32_dpp v147, v147, v147 row_mirror row_mask:0xf bank_mask:0xf bound_ctrl:1
	ds_swizzle_b32 v148, v147 offset:swizzle(SWAP,16)
	s_waitcnt lgkmcnt(0)
	v_add_f32_e32 v147, v147, v148
	v_mov_b32_e32 v148, v147
	s_nop 1
	v_permlane32_swap_b32_e32 v147, v148
	v_add_f32_e32 v147, v147, v148
	v_fmamk_f32 v147, v147, 0x3a000000, v233
	v_rsq_f32_e32 v148, v147
	s_nop 0
	v_pk_mul_f32 v[26:27], v[26:27], v[148:149] op_sel_hi:[1,0]
	s_nop 0
	s_waitcnt vmcnt(0)
	v_pk_mul_f32 v[26:27], v[110:111], v[26:27]
	v_pk_add_f32 v[110:111], v[114:115], 1.0 op_sel_hi:[1,0]
	v_pk_mul_f32 v[30:31], v[30:31], v[148:149] op_sel_hi:[1,0]
	v_pk_fma_f32 v[106:107], v[110:111], v[26:27], v[106:107]
	v_pk_mul_f32 v[26:27], v[32:33], v[148:149] op_sel_hi:[1,0]
	v_pk_add_f32 v[32:33], v[128:129], 1.0 op_sel_hi:[1,0]
	v_pk_mul_f32 v[26:27], v[124:125], v[26:27]
	v_pk_mul_f32 v[30:31], v[122:123], v[30:31]
	v_pk_add_f32 v[122:123], v[126:127], 1.0 op_sel_hi:[1,0]
	v_pk_fma_f32 v[32:33], v[32:33], v[26:27], v[120:121]
	v_pk_mul_f32 v[26:27], v[28:29], v[148:149] op_sel_hi:[1,0]
	v_pk_fma_f32 v[30:31], v[122:123], v[30:31], v[118:119]
	v_pk_mul_f32 v[26:27], v[112:113], v[26:27]
	v_pk_add_f32 v[28:29], v[116:117], 1.0 op_sel_hi:[1,0]
	v_pk_mul_f32 v[22:23], v[22:23], v[148:149] op_sel_hi:[1,0]
	v_pk_fma_f32 v[108:109], v[28:29], v[26:27], v[108:109]
	v_cvt_pk_bf16_f32 v26, v30, v31
	v_pk_mul_f32 v[22:23], v[98:99], v[22:23]
	v_pk_add_f32 v[30:31], v[102:103], 1.0 op_sel_hi:[1,0]
	v_pk_mul_f32 v[18:19], v[18:19], v[148:149] op_sel_hi:[1,0]
	v_pk_fma_f32 v[22:23], v[30:31], v[22:23], v[94:95]
	v_pk_mul_f32 v[18:19], v[86:87], v[18:19]
	v_pk_add_f32 v[30:31], v[90:91], 1.0 op_sel_hi:[1,0]
	v_pk_mul_f32 v[14:15], v[14:15], v[148:149] op_sel_hi:[1,0]
	v_pk_fma_f32 v[30:31], v[30:31], v[18:19], v[82:83]
	v_pk_mul_f32 v[18:19], v[24:25], v[148:149] op_sel_hi:[1,0]
	v_pk_add_f32 v[24:25], v[104:105], 1.0 op_sel_hi:[1,0]
	v_pk_mul_f32 v[18:19], v[100:101], v[18:19]
	v_cvt_pk_bf16_f32 v27, v32, v33
	v_pk_fma_f32 v[24:25], v[24:25], v[18:19], v[96:97]
	v_pk_mul_f32 v[18:19], v[20:21], v[148:149] op_sel_hi:[1,0]
	v_pk_add_f32 v[20:21], v[92:93], 1.0 op_sel_hi:[1,0]
	v_pk_mul_f32 v[18:19], v[88:89], v[18:19]
	v_pk_mul_f32 v[14:15], v[74:75], v[14:15]
	v_pk_fma_f32 v[32:33], v[20:21], v[18:19], v[84:85]
	v_cvt_pk_bf16_f32 v18, v22, v23
	v_pk_add_f32 v[22:23], v[78:79], 1.0 op_sel_hi:[1,0]
	v_pk_mul_f32 v[10:11], v[10:11], v[148:149] op_sel_hi:[1,0]
	v_pk_fma_f32 v[14:15], v[22:23], v[14:15], v[70:71]
	v_pk_mul_f32 v[10:11], v[62:63], v[10:11]
	v_pk_add_f32 v[22:23], v[66:67], 1.0 op_sel_hi:[1,0]
	v_pk_mul_f32 v[6:7], v[6:7], v[148:149] op_sel_hi:[1,0]
	v_pk_fma_f32 v[22:23], v[22:23], v[10:11], v[58:59]
	v_pk_mul_f32 v[10:11], v[16:17], v[148:149] op_sel_hi:[1,0]
	v_pk_add_f32 v[16:17], v[80:81], 1.0 op_sel_hi:[1,0]
	v_pk_mul_f32 v[10:11], v[76:77], v[10:11]
	v_cvt_pk_bf16_f32 v19, v24, v25
	v_pk_fma_f32 v[16:17], v[16:17], v[10:11], v[72:73]
	v_pk_mul_f32 v[10:11], v[12:13], v[148:149] op_sel_hi:[1,0]
	v_pk_add_f32 v[12:13], v[68:69], 1.0 op_sel_hi:[1,0]
	v_pk_mul_f32 v[10:11], v[64:65], v[10:11]
	v_pk_mul_f32 v[6:7], v[50:51], v[6:7]
	v_pk_fma_f32 v[24:25], v[12:13], v[10:11], v[60:61]
	v_cvt_pk_bf16_f32 v10, v14, v15
	v_pk_add_f32 v[14:15], v[54:55], 1.0 op_sel_hi:[1,0]
	v_pk_mul_f32 v[2:3], v[2:3], v[148:149] op_sel_hi:[1,0]
	v_pk_fma_f32 v[6:7], v[14:15], v[6:7], v[46:47]
	v_pk_mul_f32 v[2:3], v[38:39], v[2:3]
	v_pk_add_f32 v[14:15], v[42:43], 1.0 op_sel_hi:[1,0]
	v_cvt_pk_bf16_f32 v28, v106, v107
	v_pk_fma_f32 v[14:15], v[14:15], v[2:3], v[34:35]
	v_pk_mul_f32 v[2:3], v[8:9], v[148:149] op_sel_hi:[1,0]
	v_pk_add_f32 v[8:9], v[56:57], 1.0 op_sel_hi:[1,0]
	v_pk_mul_f32 v[2:3], v[52:53], v[2:3]
	v_cvt_pk_bf16_f32 v29, v108, v109
	v_pk_fma_f32 v[8:9], v[8:9], v[2:3], v[48:49]
	v_pk_mul_f32 v[2:3], v[4:5], v[148:149] op_sel_hi:[1,0]
	v_pk_add_f32 v[4:5], v[44:45], 1.0 op_sel_hi:[1,0]
	v_pk_mul_f32 v[2:3], v[40:41], v[2:3]
	v_cvt_pk_bf16_f32 v11, v16, v17
	v_pk_fma_f32 v[16:17], v[4:5], v[2:3], v[36:37]
	v_cvt_pk_bf16_f32 v20, v30, v31
	v_cvt_pk_bf16_f32 v21, v32, v33
	v_cvt_pk_bf16_f32 v12, v22, v23
	v_cvt_pk_bf16_f32 v13, v24, v25
	v_cvt_pk_bf16_f32 v2, v6, v7
	v_cvt_pk_bf16_f32 v3, v8, v9
	v_cvt_pk_bf16_f32 v4, v14, v15
	v_cvt_pk_bf16_f32 v5, v16, v17
	global_store_dwordx4 v[142:143], v[26:29], off
	global_store_dwordx4 v[142:143], v[18:21], off offset:1024
	global_store_dwordx4 v[142:143], v[10:13], off offset:2048
	global_store_dwordx4 v[142:143], v[2:5], off offset:3072
	v_lshl_add_u64 v[142:143], v[142:143], 0, s[56:57]
	s_cbranch_scc0 .LBB0_157

.LBB0_155:
	s_lshl_b64 s[12:13], s[12:13], 2
	s_add_u32 s12, s16, s12
	s_addc_u32 s13, s17, s13
	s_add_u32 s14, s12, 0x2000
	s_addc_u32 s15, s13, 0
	global_load_dwordx4 v[110:113], v[132:133], off offset:16
	global_load_dwordx4 v[122:125], v[132:133], off
	global_load_dwordx4 v[106:109], v0, s[12:13] offset:16
	global_load_dwordx4 v[118:121], v0, s[12:13]
	global_load_dwordx4 v[114:117], v0, s[14:15] offset:16
	global_load_dwordx4 v[126:129], v0, s[14:15]
	global_load_dwordx4 v[86:89], v[132:133], off offset:2064
	global_load_dwordx4 v[98:101], v[132:133], off offset:2048
	global_load_dwordx4 v[82:85], v0, s[12:13] offset:2064
	global_load_dwordx4 v[94:97], v0, s[12:13] offset:2048
	global_load_dwordx4 v[90:93], v144, s[14:15] offset:16
	global_load_dwordx4 v[102:105], v144, s[14:15]
	global_load_dwordx4 v[62:65], v[134:135], off offset:16
	global_load_dwordx4 v[74:77], v[134:135], off
	global_load_dwordx4 v[58:61], v145, s[12:13] offset:16
	global_load_dwordx4 v[70:73], v145, s[12:13]
	global_load_dwordx4 v[66:69], v145, s[14:15] offset:16
	global_load_dwordx4 v[78:81], v145, s[14:15]
	global_load_dwordx4 v[38:41], v[136:137], off offset:16
	global_load_dwordx4 v[50:53], v[136:137], off
	global_load_dwordx4 v[34:37], v146, s[12:13] offset:16
	global_load_dwordx4 v[46:49], v146, s[12:13]
	global_load_dwordx4 v[42:45], v146, s[14:15] offset:16
	global_load_dwordx4 v[54:57], v146, s[14:15]
	s_and_b64 vcc, exec, s[4:5]
	s_cbranch_vccnz .LBB0_148
	s_mov_b32 s7, s47
	s_lshl_b64 s[4:5], s[6:7], 12
	s_waitcnt vmcnt(0)
	v_cvt_pk_bf16_f32 v148, v30, v31
	v_cvt_pk_bf16_f32 v149, v32, v33
	v_cvt_pk_bf16_f32 v150, v26, v27
	v_cvt_pk_bf16_f32 v151, v28, v29
	v_lshl_add_u64 v[152:153], v[140:141], 0, s[4:5]
	global_store_dwordx4 v[152:153], v[148:151], off
	s_nop 1
	v_cvt_pk_bf16_f32 v148, v22, v23
	v_cvt_pk_bf16_f32 v149, v24, v25
	v_cvt_pk_bf16_f32 v150, v18, v19
	v_cvt_pk_bf16_f32 v151, v20, v21
	global_store_dwordx4 v[152:153], v[148:151], off offset:1024
	s_nop 1
	v_cvt_pk_bf16_f32 v148, v14, v15
	v_cvt_pk_bf16_f32 v149, v16, v17
	v_cvt_pk_bf16_f32 v150, v10, v11
	v_cvt_pk_bf16_f32 v151, v12, v13
	global_store_dwordx4 v[152:153], v[148:151], off offset:2048
	s_nop 1
	v_cvt_pk_bf16_f32 v148, v6, v7
	v_cvt_pk_bf16_f32 v149, v8, v9
	v_cvt_pk_bf16_f32 v150, v2, v3
	v_cvt_pk_bf16_f32 v151, v4, v5
	global_store_dwordx4 v[152:153], v[148:151], off offset:3072
	s_nop 1
	s_branch .LBB0_148
